# same as the adjacent-row post version plus one defensive wait state after a VALU write feeding an SDWA multiply in the foxc pass
# baseline (speedup 1.0000x reference)
.Lfc_loop:
	v_mul_u32_u24_sdwa v23, v14, s16 dst_sel:DWORD dst_unused:UNUSED_PAD src0_sel:WORD_0 src1_sel:DWORD
	v_lshrrev_b32_e32 v15, 19, v23
	v_mul_lo_u16_e32 v23, 0x82, v15
	v_sub_u16_e32 v16, v14, v23
	v_mul_u32_u24_e32 v23, 0x82, v15
	v_add_lshl_u32 v178, v23, v176, 2
	v_lshrrev_b32_e32 v23, 3, v15
	v_and_b32_e32 v24, 7, v15
	v_lshl_add_u64 v[26:27], s[68:69], 0, v[178:179]
	v_lshl_or_b32 v0, v16, 6, v176
	global_load_dword v20, v[26:27], off
	global_load_dword v21, v[26:27], off offset:256
	global_load_dword v22, v[26:27], off offset:512
	v_mad_u32_u24 v23, v23, s9, v0
	v_mul_u32_u24_e32 v23, 0x1618, v23
	v_or_b32_e32 v178, v23, v24
	v_lshl_add_u64 v[26:27], v[178:179], 1, s[56:57]
	v_or_b32_e32 v178, s8, v24
	global_load_ushort v25, v[26:27], off offset:3072
	v_lshl_add_u64 v[26:27], v[178:179], 2, s[70:71]
	global_load_dword v26, v[26:27], off
	v_add_u32_e32 v28, s33, v14
	s_nop 0
	v_readfirstlane_b32 s6, v28
	s_cmp_le_u32 s6, s37
	s_cselect_b32 s7, 1, 0
	s_min_u32 s6, s6, s37
	v_mov_b32_e32 v28, s6
	s_nop 1
	v_mul_u32_u24_sdwa v37, v28, s16 dst_sel:DWORD dst_unused:UNUSED_PAD src0_sel:WORD_0 src1_sel:DWORD
	v_lshrrev_b32_e32 v29, 19, v37
	v_mul_lo_u16_e32 v37, 0x82, v29
	v_sub_u16_e32 v30, v28, v37
	v_mul_u32_u24_e32 v37, 0x82, v29
	v_add_lshl_u32 v178, v37, v176, 2
	v_lshrrev_b32_e32 v37, 3, v29
	v_and_b32_e32 v38, 7, v29
	v_lshl_add_u64 v[40:41], s[68:69], 0, v[178:179]
	v_lshl_or_b32 v31, v30, 6, v176
	global_load_dword v32, v[40:41], off
	global_load_dword v33, v[40:41], off offset:256
	global_load_dword v34, v[40:41], off offset:512
	v_mad_u32_u24 v37, v37, s9, v31
	v_mul_u32_u24_e32 v37, 0x1618, v37
	v_or_b32_e32 v178, v37, v38
	v_lshl_add_u64 v[40:41], v[178:179], 1, s[56:57]
	v_or_b32_e32 v178, s8, v38
	global_load_ushort v35, v[40:41], off offset:3072
	v_lshl_add_u64 v[40:41], v[178:179], 2, s[70:71]
	global_load_dword v36, v[40:41], off
	s_waitcnt vmcnt(7)
	v_cmp_lt_u32_e32 vcc, v176, v16
	s_nop 1
	v_cndmask_b32_e32 v17, 0, v20, vcc
	v_add_f32_e32 v17, 0, v17
	v_cmp_lt_u32_e32 vcc, v215, v16
	s_nop 1
	v_cndmask_b32_e32 v18, 0, v21, vcc
	v_add_f32_e32 v17, v17, v18
	v_cmp_lt_u32_e32 vcc, v216, v16
	s_nop 1
	v_cndmask_b32_e32 v18, 0, v22, vcc
	v_add_f32_e32 v17, v17, v18
	ds_bpermute_b32 v18, v2, v17
	s_waitcnt lgkmcnt(0)
	v_add_f32_e32 v18, v17, v18
	ds_bpermute_b32 v19, v3, v18
	s_waitcnt lgkmcnt(0)
	v_add_f32_e32 v18, v18, v19
	ds_bpermute_b32 v19, v4, v18
	s_waitcnt lgkmcnt(0)
	v_add_f32_e32 v18, v18, v19
	ds_bpermute_b32 v19, v5, v18
	s_waitcnt lgkmcnt(0)
	v_add_f32_e32 v18, v18, v19
	ds_bpermute_b32 v19, v6, v18
	s_waitcnt lgkmcnt(0)
	v_add_f32_e32 v1, v18, v19
	ds_bpermute_b32 v17, v7, v1
	s_waitcnt vmcnt(5)
	v_lshlrev_b32_e32 v25, 16, v25
	v_add_f32_e32 v25, v26, v25
	v_mul_f32_e64 v26, |v25|, s98
	v_exp_f32_e32 v26, v26
	v_min_f32_e32 v25, 0, v25
	v_add_f32_e32 v26, 1.0, v26
	v_log_f32_e32 v26, v26
	s_nop 0
	v_fmac_f32_e32 v25, 0xbf317218, v26
	v_cmp_lt_u32_e32 vcc, s46, v0
	s_nop 1
	v_cndmask_b32_e32 v16, 0, v25, vcc
	s_waitcnt lgkmcnt(0)
	v_add_f32_e32 v1, v1, v17
	ds_bpermute_b32 v17, v8, v16
	v_mul_u32_u24_e32 v15, 0x2080, v15
	s_waitcnt lgkmcnt(0)
	v_add_f32_e32 v17, v16, v17
	v_cndmask_b32_e64 v16, v17, v16, s[72:73]
	ds_bpermute_b32 v17, v9, v16
	v_add_lshl_u32 v0, v0, v15, 2
	s_waitcnt lgkmcnt(0)
	v_add_f32_e32 v17, v16, v17
	v_cndmask_b32_e64 v16, v17, v16, s[74:75]
	ds_bpermute_b32 v17, v10, v16
	s_waitcnt lgkmcnt(0)
	v_add_f32_e32 v17, v16, v17
	v_cndmask_b32_e64 v16, v17, v16, s[76:77]
	ds_bpermute_b32 v17, v11, v16
	s_waitcnt lgkmcnt(0)
	v_add_f32_e32 v17, v16, v17
	v_cndmask_b32_e64 v16, v17, v16, s[78:79]
	ds_bpermute_b32 v17, v12, v16
	s_waitcnt lgkmcnt(0)
	v_add_f32_e32 v17, v16, v17
	v_cndmask_b32_e64 v16, v17, v16, s[80:81]
	ds_bpermute_b32 v17, v13, v16
	s_waitcnt lgkmcnt(0)
	v_add_f32_e32 v17, v16, v17
	v_cndmask_b32_e64 v16, v17, v16, s[82:83]
	v_add_f32_e32 v1, v1, v16
	global_store_dword v0, v1, s[60:61]
	s_cmp_eq_u32 s7, 0
	s_cbranch_scc1 .Lfc_noB
	s_waitcnt vmcnt(3)
	v_cmp_lt_u32_e32 vcc, v176, v30
	s_nop 1
	v_cndmask_b32_e32 v17, 0, v32, vcc
	v_add_f32_e32 v17, 0, v17
	v_cmp_lt_u32_e32 vcc, v215, v30
	s_nop 1
	v_cndmask_b32_e32 v18, 0, v33, vcc
	v_add_f32_e32 v17, v17, v18
	v_cmp_lt_u32_e32 vcc, v216, v30
	s_nop 1
	v_cndmask_b32_e32 v18, 0, v34, vcc
	v_add_f32_e32 v17, v17, v18
	ds_bpermute_b32 v18, v2, v17
	s_waitcnt lgkmcnt(0)
	v_add_f32_e32 v18, v17, v18
	ds_bpermute_b32 v19, v3, v18
	s_waitcnt lgkmcnt(0)
	v_add_f32_e32 v18, v18, v19
	ds_bpermute_b32 v19, v4, v18
	s_waitcnt lgkmcnt(0)
	v_add_f32_e32 v18, v18, v19
	ds_bpermute_b32 v19, v5, v18
	s_waitcnt lgkmcnt(0)
	v_add_f32_e32 v18, v18, v19
	ds_bpermute_b32 v19, v6, v18
	s_waitcnt lgkmcnt(0)
	v_add_f32_e32 v1, v18, v19
	ds_bpermute_b32 v17, v7, v1
	s_waitcnt vmcnt(1)
	v_lshlrev_b32_e32 v35, 16, v35
	v_add_f32_e32 v35, v36, v35
	v_mul_f32_e64 v36, |v35|, s98
	v_exp_f32_e32 v36, v36
	v_min_f32_e32 v35, 0, v35
	v_add_f32_e32 v36, 1.0, v36
	v_log_f32_e32 v36, v36
	s_nop 0
	v_fmac_f32_e32 v35, 0xbf317218, v36
	v_cmp_lt_u32_e32 vcc, s46, v31
	s_nop 1
	v_cndmask_b32_e32 v30, 0, v35, vcc
	s_waitcnt lgkmcnt(0)
	v_add_f32_e32 v1, v1, v17
	ds_bpermute_b32 v17, v8, v30
	v_mul_u32_u24_e32 v29, 0x2080, v29
	s_waitcnt lgkmcnt(0)
	v_add_f32_e32 v17, v30, v17
	v_cndmask_b32_e64 v30, v17, v30, s[72:73]
	ds_bpermute_b32 v17, v9, v30
	v_add_lshl_u32 v31, v31, v29, 2
	s_waitcnt lgkmcnt(0)
	v_add_f32_e32 v17, v30, v17
	v_cndmask_b32_e64 v30, v17, v30, s[74:75]
	ds_bpermute_b32 v17, v10, v30
	s_waitcnt lgkmcnt(0)
	v_add_f32_e32 v17, v30, v17
	v_cndmask_b32_e64 v30, v17, v30, s[76:77]
	ds_bpermute_b32 v17, v11, v30
	s_waitcnt lgkmcnt(0)
	v_add_f32_e32 v17, v30, v17
	v_cndmask_b32_e64 v30, v17, v30, s[78:79]
	ds_bpermute_b32 v17, v12, v30
	s_waitcnt lgkmcnt(0)
	v_add_f32_e32 v17, v30, v17
	v_cndmask_b32_e64 v30, v17, v30, s[80:81]
	ds_bpermute_b32 v17, v13, v30
	s_waitcnt lgkmcnt(0)
	v_add_f32_e32 v17, v30, v17
	v_cndmask_b32_e64 v30, v17, v30, s[82:83]
	v_add_f32_e32 v1, v1, v30
	global_store_dword v31, v1, s[60:61]
